# v093 + RG-LRU tile-top barrier dropped (ordering already given by the barrier before the Y-store block) + scan register/address setup moved in front of the pre-scan barrier
# baseline (speedup 1.0000x reference)
; #define LAS __attribute__((address_space(3)))
; DI unsigned pk2(float a, float b) { f32x2 v = {a, b}; bf2_t r = __builtin_convertvector(v, bf2_t); return __builtin_bit_cast(unsigned, r); }
; DI void phase_rglru(const Params& p, unsigned char* shm) {
;     ...
;             __syncthreads();
;             if (tid < 192) {
; #pragma unroll 8
;                 for (int r = 0; r < 64; ++r) {
;                     const float om = __uint_as_float((unsigned)*(const LAS bf16_t*)(lds + LAo + r * TR + tid * 2) << 16);
;                     const float bt = __uint_as_float((unsigned)*(const LAS bf16_t*)(lds + BTo + r * TR + tid * 2) << 16);
;                     const float g = __uint_as_float((unsigned)*(const LAS bf16_t*)(lds + GT + r * TR + tid * 2) << 16);
;                     hst = (hst - om * hst) + bt;
;                     *(LAS bf16_t*)(lds + GT + r * TR + tid * 2) = (bf16_t)(pk2(hst * g, 0.f) & 0xffffu);
;                 }
;             } else if (tid >= 256 && tid < 328) {
;                 const int i = tid - 256, r = i / 24, cc = i % 24;
;                 const u32x4 v = *(const LAS u32x4*)(lds + XR + (64 + r) * TR + cc * 16);
;                 *(LAS u32x4*)(lds + XR + r * TR + cc * 16) = v;
;             }
.LBB0_847:
	s_waitcnt lgkmcnt(0)
	v_mov_b32_e32 v126, 0
	v_mov_b32_e32 v127, 0
	v_mov_b32_e32 v128, 0
	v_mov_b32_e32 v129, 0
	v_mov_b32_e32 v130, 0
	v_mov_b32_e32 v131, 0
	v_mov_b32_e32 v132, 0
	v_mov_b32_e32 v133, 0
	v_mov_b32_e32 v134, 0
	v_mov_b32_e32 v135, 0
	v_mov_b32_e32 v136, 0
	v_mov_b32_e32 v137, 0
	v_mov_b32_e32 v138, 0
	v_mov_b32_e32 v139, 0
	v_mov_b32_e32 v140, 0
	v_mov_b32_e32 v141, 0
	v_mov_b32_e32 v142, 0
	v_mov_b32_e32 v143, 0
	v_mov_b32_e32 v144, 0
	v_mov_b32_e32 v145, 0
	v_mov_b32_e32 v146, 0
	v_mov_b32_e32 v147, 0
	v_mov_b32_e32 v148, 0
	v_mov_b32_e32 v149, 0
	v_add_u32_e32 v121, 0x13100, v176
	v_add_u32_e32 v122, 0x19500, v176
	v_add_u32_e32 v123, 0xcd00, v176
	v_lshlrev_b32_e32 v124, 1, v176
	v_add_u32_e32 v124, 0x6900, v124
	s_barrier
	s_and_saveexec_b64 s[2:3], s[48:49]
	s_xor_b64 s[2:3], exec, s[2:3]
	s_cbranch_execz .LBB0_851
	s_and_saveexec_b64 s[28:29], s[50:51]
	s_cbranch_execz .LBB0_850
	ds_read_b128 v[120:123], v200 offset:25600
	s_waitcnt lgkmcnt(0)
	ds_write_b128 v200, v[120:123]

; #define LAS __attribute__((address_space(3)))
; DI unsigned pk2(float a, float b) { f32x2 v = {a, b}; bf2_t r = __builtin_convertvector(v, bf2_t); return __builtin_bit_cast(unsigned, r); }
; DI void phase_rglru(const Params& p, unsigned char* shm) {
;     ...
;             if (tid < 192) {
; #pragma unroll 8
;                 for (int r = 0; r < 64; ++r) {
;                     const float om = __uint_as_float((unsigned)*(const LAS bf16_t*)(lds + LAo + r * TR + tid * 2) << 16);
;                     const float bt = __uint_as_float((unsigned)*(const LAS bf16_t*)(lds + BTo + r * TR + tid * 2) << 16);
;                     const float g = __uint_as_float((unsigned)*(const LAS bf16_t*)(lds + GT + r * TR + tid * 2) << 16);
;                     hst = (hst - om * hst) + bt;
;                     *(LAS bf16_t*)(lds + GT + r * TR + tid * 2) = (bf16_t)(pk2(hst * g, 0.f) & 0xffffu);
;                 }
.LBB0_851:
	s_andn2_saveexec_b64 s[2:3], s[2:3]
	s_cbranch_execz .LBB0_842
	ds_read_u16_d16_hi v126, v121
	ds_read_u16_d16_hi v134, v122
	ds_read_u16_d16_hi v142, v123
	ds_read_u16_d16_hi v127, v121 offset:400
	ds_read_u16_d16_hi v135, v122 offset:400
	ds_read_u16_d16_hi v143, v123 offset:400
	ds_read_u16_d16_hi v128, v121 offset:800
	ds_read_u16_d16_hi v136, v122 offset:800
	ds_read_u16_d16_hi v144, v123 offset:800
	ds_read_u16_d16_hi v129, v121 offset:1200
	ds_read_u16_d16_hi v137, v122 offset:1200
	ds_read_u16_d16_hi v145, v123 offset:1200
	ds_read_u16_d16_hi v130, v121 offset:1600
	ds_read_u16_d16_hi v138, v122 offset:1600
	ds_read_u16_d16_hi v146, v123 offset:1600
	s_waitcnt lgkmcnt(12)
	v_fma_f32 v150, -v152, v126, v152
	v_add_f32_e32 v152, v150, v134
	v_mul_f32_e32 v170, v152, v142
	ds_read_u16_d16_hi v131, v121 offset:2000
	ds_read_u16_d16_hi v139, v122 offset:2000
	ds_read_u16_d16_hi v147, v123 offset:2000
	s_waitcnt lgkmcnt(12)
	v_fma_f32 v150, -v152, v127, v152
	v_add_f32_e32 v152, v150, v135
	v_mul_f32_e32 v171, v152, v143
	ds_read_u16_d16_hi v132, v121 offset:2400
	ds_read_u16_d16_hi v140, v122 offset:2400
	ds_read_u16_d16_hi v148, v123 offset:2400
	v_cvt_pk_bf16_f32 v151, v170, v171
	ds_write_b32 v124, v151
	s_waitcnt lgkmcnt(13)
	v_fma_f32 v150, -v152, v128, v152
	v_add_f32_e32 v152, v150, v136
	v_mul_f32_e32 v170, v152, v144
	ds_read_u16_d16_hi v133, v121 offset:2800
	ds_read_u16_d16_hi v141, v122 offset:2800
	ds_read_u16_d16_hi v149, v123 offset:2800
	s_waitcnt lgkmcnt(13)
	v_fma_f32 v150, -v152, v129, v152
	v_add_f32_e32 v152, v150, v137
	v_mul_f32_e32 v171, v152, v145
	ds_read_u16_d16_hi v126, v121 offset:3200
	ds_read_u16_d16_hi v134, v122 offset:3200
	ds_read_u16_d16_hi v142, v123 offset:3200
	v_cvt_pk_bf16_f32 v151, v170, v171
	ds_write_b32 v124, v151 offset:800
	s_waitcnt lgkmcnt(14)
	v_fma_f32 v150, -v152, v130, v152
	v_add_f32_e32 v152, v150, v138
	v_mul_f32_e32 v170, v152, v146
	ds_read_u16_d16_hi v127, v121 offset:3600
	ds_read_u16_d16_hi v135, v122 offset:3600
	ds_read_u16_d16_hi v143, v123 offset:3600
	s_waitcnt lgkmcnt(14)
	v_fma_f32 v150, -v152, v131, v152
	v_add_f32_e32 v152, v150, v139
	v_mul_f32_e32 v171, v152, v147
	ds_read_u16_d16_hi v128, v121 offset:4000
	ds_read_u16_d16_hi v136, v122 offset:4000
	ds_read_u16_d16_hi v144, v123 offset:4000
	v_cvt_pk_bf16_f32 v151, v170, v171
	ds_write_b32 v124, v151 offset:1600
	s_waitcnt lgkmcnt(15)
	v_fma_f32 v150, -v152, v132, v152
	v_add_f32_e32 v152, v150, v140
	v_mul_f32_e32 v170, v152, v148
	ds_read_u16_d16_hi v129, v121 offset:4400
	ds_read_u16_d16_hi v137, v122 offset:4400
	ds_read_u16_d16_hi v145, v123 offset:4400
	s_waitcnt lgkmcnt(14)
	v_fma_f32 v150, -v152, v133, v152
	v_add_f32_e32 v152, v150, v141
	v_mul_f32_e32 v171, v152, v149
	ds_read_u16_d16_hi v130, v121 offset:4800
	ds_read_u16_d16_hi v138, v122 offset:4800
	ds_read_u16_d16_hi v146, v123 offset:4800
	v_cvt_pk_bf16_f32 v151, v170, v171
	ds_write_b32 v124, v151 offset:2400
	s_waitcnt lgkmcnt(15)
	v_fma_f32 v150, -v152, v126, v152
	v_add_f32_e32 v152, v150, v134
	v_mul_f32_e32 v170, v152, v142
	ds_read_u16_d16_hi v131, v121 offset:5200
	ds_read_u16_d16_hi v139, v122 offset:5200
	ds_read_u16_d16_hi v147, v123 offset:5200
	s_waitcnt lgkmcnt(14)
	v_fma_f32 v150, -v152, v127, v152
	v_add_f32_e32 v152, v150, v135
	v_mul_f32_e32 v171, v152, v143
	ds_read_u16_d16_hi v132, v121 offset:5600
	ds_read_u16_d16_hi v140, v122 offset:5600
	ds_read_u16_d16_hi v148, v123 offset:5600
	v_cvt_pk_bf16_f32 v151, v170, v171
	ds_write_b32 v124, v151 offset:3200
	s_waitcnt lgkmcnt(15)
	v_fma_f32 v150, -v152, v128, v152
	v_add_f32_e32 v152, v150, v136
	v_mul_f32_e32 v170, v152, v144
	ds_read_u16_d16_hi v133, v121 offset:6000
	ds_read_u16_d16_hi v141, v122 offset:6000
	ds_read_u16_d16_hi v149, v123 offset:6000
	s_waitcnt lgkmcnt(14)
	v_fma_f32 v150, -v152, v129, v152
	v_add_f32_e32 v152, v150, v137
	v_mul_f32_e32 v171, v152, v145
	ds_read_u16_d16_hi v126, v121 offset:6400
	ds_read_u16_d16_hi v134, v122 offset:6400
	ds_read_u16_d16_hi v142, v123 offset:6400
	v_cvt_pk_bf16_f32 v151, v170, v171
	ds_write_b32 v124, v151 offset:4000
	s_waitcnt lgkmcnt(15)
	v_fma_f32 v150, -v152, v130, v152
	v_add_f32_e32 v152, v150, v138
	v_mul_f32_e32 v170, v152, v146
	ds_read_u16_d16_hi v127, v121 offset:6800
	ds_read_u16_d16_hi v135, v122 offset:6800
	ds_read_u16_d16_hi v143, v123 offset:6800
	s_waitcnt lgkmcnt(14)
	v_fma_f32 v150, -v152, v131, v152
	v_add_f32_e32 v152, v150, v139
	v_mul_f32_e32 v171, v152, v147
	ds_read_u16_d16_hi v128, v121 offset:7200
	ds_read_u16_d16_hi v136, v122 offset:7200
	ds_read_u16_d16_hi v144, v123 offset:7200
	v_cvt_pk_bf16_f32 v151, v170, v171
	ds_write_b32 v124, v151 offset:4800
	s_waitcnt lgkmcnt(15)
	v_fma_f32 v150, -v152, v132, v152
	v_add_f32_e32 v152, v150, v140
	v_mul_f32_e32 v170, v152, v148
	ds_read_u16_d16_hi v129, v121 offset:7600
	ds_read_u16_d16_hi v137, v122 offset:7600
	ds_read_u16_d16_hi v145, v123 offset:7600
	s_waitcnt lgkmcnt(14)
	v_fma_f32 v150, -v152, v133, v152
	v_add_f32_e32 v152, v150, v141
	v_mul_f32_e32 v171, v152, v149
	ds_read_u16_d16_hi v130, v121 offset:8000
	ds_read_u16_d16_hi v138, v122 offset:8000
	ds_read_u16_d16_hi v146, v123 offset:8000
	v_cvt_pk_bf16_f32 v151, v170, v171
	ds_write_b32 v124, v151 offset:5600
	s_waitcnt lgkmcnt(15)
	v_fma_f32 v150, -v152, v126, v152
	v_add_f32_e32 v152, v150, v134
	v_mul_f32_e32 v170, v152, v142
	ds_read_u16_d16_hi v131, v121 offset:8400
	ds_read_u16_d16_hi v139, v122 offset:8400
	ds_read_u16_d16_hi v147, v123 offset:8400
	s_waitcnt lgkmcnt(14)
; #define LAS __attribute__((address_space(3)))
; DI unsigned pk2(float a, float b) { f32x2 v = {a, b}; bf2_t r = __builtin_convertvector(v, bf2_t); return __builtin_bit_cast(unsigned, r); }
; DI void phase_rglru(const Params& p, unsigned char* shm) {
;     ...
;             if (tid < 192) {
; #pragma unroll 8
;                 for (int r = 0; r < 64; ++r) {
;                     const float om = __uint_as_float((unsigned)*(const LAS bf16_t*)(lds + LAo + r * TR + tid * 2) << 16);
;                     const float bt = __uint_as_float((unsigned)*(const LAS bf16_t*)(lds + BTo + r * TR + tid * 2) << 16);
;                     const float g = __uint_as_float((unsigned)*(const LAS bf16_t*)(lds + GT + r * TR + tid * 2) << 16);
;                     hst = (hst - om * hst) + bt;
;                     *(LAS bf16_t*)(lds + GT + r * TR + tid * 2) = (bf16_t)(pk2(hst * g, 0.f) & 0xffffu);
;                 }
	v_fma_f32 v150, -v152, v127, v152
	v_add_f32_e32 v152, v150, v135
	v_mul_f32_e32 v171, v152, v143
	ds_read_u16_d16_hi v132, v121 offset:8800
	ds_read_u16_d16_hi v140, v122 offset:8800
	ds_read_u16_d16_hi v148, v123 offset:8800
	v_cvt_pk_bf16_f32 v151, v170, v171
	ds_write_b32 v124, v151 offset:6400
	s_waitcnt lgkmcnt(15)
	v_fma_f32 v150, -v152, v128, v152
	v_add_f32_e32 v152, v150, v136
	v_mul_f32_e32 v170, v152, v144
	ds_read_u16_d16_hi v133, v121 offset:9200
	ds_read_u16_d16_hi v141, v122 offset:9200
	ds_read_u16_d16_hi v149, v123 offset:9200
	s_waitcnt lgkmcnt(14)
	v_fma_f32 v150, -v152, v129, v152
	v_add_f32_e32 v152, v150, v137
	v_mul_f32_e32 v171, v152, v145
	ds_read_u16_d16_hi v126, v121 offset:9600
	ds_read_u16_d16_hi v134, v122 offset:9600
	ds_read_u16_d16_hi v142, v123 offset:9600
	v_cvt_pk_bf16_f32 v151, v170, v171
	ds_write_b32 v124, v151 offset:7200
	s_waitcnt lgkmcnt(15)
	v_fma_f32 v150, -v152, v130, v152
	v_add_f32_e32 v152, v150, v138
	v_mul_f32_e32 v170, v152, v146
	ds_read_u16_d16_hi v127, v121 offset:10000
	ds_read_u16_d16_hi v135, v122 offset:10000
	ds_read_u16_d16_hi v143, v123 offset:10000
	s_waitcnt lgkmcnt(14)
	v_fma_f32 v150, -v152, v131, v152
	v_add_f32_e32 v152, v150, v139
	v_mul_f32_e32 v171, v152, v147
	ds_read_u16_d16_hi v128, v121 offset:10400
	ds_read_u16_d16_hi v136, v122 offset:10400
	ds_read_u16_d16_hi v144, v123 offset:10400
	v_cvt_pk_bf16_f32 v151, v170, v171
	ds_write_b32 v124, v151 offset:8000
	s_waitcnt lgkmcnt(15)
	v_fma_f32 v150, -v152, v132, v152
	v_add_f32_e32 v152, v150, v140
	v_mul_f32_e32 v170, v152, v148
	ds_read_u16_d16_hi v129, v121 offset:10800
	ds_read_u16_d16_hi v137, v122 offset:10800
	ds_read_u16_d16_hi v145, v123 offset:10800
	s_waitcnt lgkmcnt(14)
	v_fma_f32 v150, -v152, v133, v152
	v_add_f32_e32 v152, v150, v141
	v_mul_f32_e32 v171, v152, v149
	ds_read_u16_d16_hi v130, v121 offset:11200
	ds_read_u16_d16_hi v138, v122 offset:11200
	ds_read_u16_d16_hi v146, v123 offset:11200
	v_cvt_pk_bf16_f32 v151, v170, v171
	ds_write_b32 v124, v151 offset:8800
	s_waitcnt lgkmcnt(15)
	v_fma_f32 v150, -v152, v126, v152
	v_add_f32_e32 v152, v150, v134
	v_mul_f32_e32 v170, v152, v142
	ds_read_u16_d16_hi v131, v121 offset:11600
	ds_read_u16_d16_hi v139, v122 offset:11600
	ds_read_u16_d16_hi v147, v123 offset:11600
	s_waitcnt lgkmcnt(14)
	v_fma_f32 v150, -v152, v127, v152
	v_add_f32_e32 v152, v150, v135
	v_mul_f32_e32 v171, v152, v143
	ds_read_u16_d16_hi v132, v121 offset:12000
	ds_read_u16_d16_hi v140, v122 offset:12000
	ds_read_u16_d16_hi v148, v123 offset:12000
	v_cvt_pk_bf16_f32 v151, v170, v171
	ds_write_b32 v124, v151 offset:9600
	s_waitcnt lgkmcnt(15)
	v_fma_f32 v150, -v152, v128, v152
	v_add_f32_e32 v152, v150, v136
	v_mul_f32_e32 v170, v152, v144
	ds_read_u16_d16_hi v133, v121 offset:12400
	ds_read_u16_d16_hi v141, v122 offset:12400
	ds_read_u16_d16_hi v149, v123 offset:12400
	s_waitcnt lgkmcnt(14)
	v_fma_f32 v150, -v152, v129, v152
	v_add_f32_e32 v152, v150, v137
	v_mul_f32_e32 v171, v152, v145
	ds_read_u16_d16_hi v126, v121 offset:12800
	ds_read_u16_d16_hi v134, v122 offset:12800
	ds_read_u16_d16_hi v142, v123 offset:12800
	v_cvt_pk_bf16_f32 v151, v170, v171
	ds_write_b32 v124, v151 offset:10400
	s_waitcnt lgkmcnt(15)
	v_fma_f32 v150, -v152, v130, v152
	v_add_f32_e32 v152, v150, v138
	v_mul_f32_e32 v170, v152, v146
	ds_read_u16_d16_hi v127, v121 offset:13200
	ds_read_u16_d16_hi v135, v122 offset:13200
	ds_read_u16_d16_hi v143, v123 offset:13200
	s_waitcnt lgkmcnt(14)
	v_fma_f32 v150, -v152, v131, v152
	v_add_f32_e32 v152, v150, v139
	v_mul_f32_e32 v171, v152, v147
	ds_read_u16_d16_hi v128, v121 offset:13600
	ds_read_u16_d16_hi v136, v122 offset:13600
	ds_read_u16_d16_hi v144, v123 offset:13600
	v_cvt_pk_bf16_f32 v151, v170, v171
	ds_write_b32 v124, v151 offset:11200
	s_waitcnt lgkmcnt(15)
	v_fma_f32 v150, -v152, v132, v152
	v_add_f32_e32 v152, v150, v140
	v_mul_f32_e32 v170, v152, v148
	ds_read_u16_d16_hi v129, v121 offset:14000
	ds_read_u16_d16_hi v137, v122 offset:14000
	ds_read_u16_d16_hi v145, v123 offset:14000
	s_waitcnt lgkmcnt(14)
	v_fma_f32 v150, -v152, v133, v152
	v_add_f32_e32 v152, v150, v141
	v_mul_f32_e32 v171, v152, v149
	ds_read_u16_d16_hi v130, v121 offset:14400
	ds_read_u16_d16_hi v138, v122 offset:14400
	ds_read_u16_d16_hi v146, v123 offset:14400
	v_cvt_pk_bf16_f32 v151, v170, v171
	ds_write_b32 v124, v151 offset:12000
	s_waitcnt lgkmcnt(15)
	v_fma_f32 v150, -v152, v126, v152
	v_add_f32_e32 v152, v150, v134
	v_mul_f32_e32 v170, v152, v142
	ds_read_u16_d16_hi v131, v121 offset:14800
	ds_read_u16_d16_hi v139, v122 offset:14800
	ds_read_u16_d16_hi v147, v123 offset:14800
	s_waitcnt lgkmcnt(14)
	v_fma_f32 v150, -v152, v127, v152
	v_add_f32_e32 v152, v150, v135
	v_mul_f32_e32 v171, v152, v143
	ds_read_u16_d16_hi v132, v121 offset:15200
	ds_read_u16_d16_hi v140, v122 offset:15200
	ds_read_u16_d16_hi v148, v123 offset:15200
	v_cvt_pk_bf16_f32 v151, v170, v171
	ds_write_b32 v124, v151 offset:12800
	s_waitcnt lgkmcnt(15)
	v_fma_f32 v150, -v152, v128, v152
	v_add_f32_e32 v152, v150, v136
	v_mul_f32_e32 v170, v152, v144
	ds_read_u16_d16_hi v133, v121 offset:15600
	ds_read_u16_d16_hi v141, v122 offset:15600
	ds_read_u16_d16_hi v149, v123 offset:15600
	s_waitcnt lgkmcnt(14)
	v_fma_f32 v150, -v152, v129, v152
	v_add_f32_e32 v152, v150, v137
	v_mul_f32_e32 v171, v152, v145
	ds_read_u16_d16_hi v126, v121 offset:16000
	ds_read_u16_d16_hi v134, v122 offset:16000
	ds_read_u16_d16_hi v142, v123 offset:16000
	v_cvt_pk_bf16_f32 v151, v170, v171
	ds_write_b32 v124, v151 offset:13600
	s_waitcnt lgkmcnt(15)
; #define LAS __attribute__((address_space(3)))
; DI unsigned pk2(float a, float b) { f32x2 v = {a, b}; bf2_t r = __builtin_convertvector(v, bf2_t); return __builtin_bit_cast(unsigned, r); }
; DI void phase_rglru(const Params& p, unsigned char* shm) {
;     ...
;             if (tid < 192) {
; #pragma unroll 8
;                 for (int r = 0; r < 64; ++r) {
;                     const float om = __uint_as_float((unsigned)*(const LAS bf16_t*)(lds + LAo + r * TR + tid * 2) << 16);
;                     const float bt = __uint_as_float((unsigned)*(const LAS bf16_t*)(lds + BTo + r * TR + tid * 2) << 16);
;                     const float g = __uint_as_float((unsigned)*(const LAS bf16_t*)(lds + GT + r * TR + tid * 2) << 16);
;                     hst = (hst - om * hst) + bt;
;                     *(LAS bf16_t*)(lds + GT + r * TR + tid * 2) = (bf16_t)(pk2(hst * g, 0.f) & 0xffffu);
;                 }
	v_fma_f32 v150, -v152, v130, v152
	v_add_f32_e32 v152, v150, v138
	v_mul_f32_e32 v170, v152, v146
	ds_read_u16_d16_hi v127, v121 offset:16400
	ds_read_u16_d16_hi v135, v122 offset:16400
	ds_read_u16_d16_hi v143, v123 offset:16400
	s_waitcnt lgkmcnt(14)
	v_fma_f32 v150, -v152, v131, v152
	v_add_f32_e32 v152, v150, v139
	v_mul_f32_e32 v171, v152, v147
	ds_read_u16_d16_hi v128, v121 offset:16800
	ds_read_u16_d16_hi v136, v122 offset:16800
	ds_read_u16_d16_hi v144, v123 offset:16800
	v_cvt_pk_bf16_f32 v151, v170, v171
	ds_write_b32 v124, v151 offset:14400
	s_waitcnt lgkmcnt(15)
	v_fma_f32 v150, -v152, v132, v152
	v_add_f32_e32 v152, v150, v140
	v_mul_f32_e32 v170, v152, v148
	ds_read_u16_d16_hi v129, v121 offset:17200
	ds_read_u16_d16_hi v137, v122 offset:17200
	ds_read_u16_d16_hi v145, v123 offset:17200
	s_waitcnt lgkmcnt(14)
	v_fma_f32 v150, -v152, v133, v152
	v_add_f32_e32 v152, v150, v141
	v_mul_f32_e32 v171, v152, v149
	ds_read_u16_d16_hi v130, v121 offset:17600
	ds_read_u16_d16_hi v138, v122 offset:17600
	ds_read_u16_d16_hi v146, v123 offset:17600
	v_cvt_pk_bf16_f32 v151, v170, v171
	ds_write_b32 v124, v151 offset:15200
	s_waitcnt lgkmcnt(15)
	v_fma_f32 v150, -v152, v126, v152
	v_add_f32_e32 v152, v150, v134
	v_mul_f32_e32 v170, v152, v142
	ds_read_u16_d16_hi v131, v121 offset:18000
	ds_read_u16_d16_hi v139, v122 offset:18000
	ds_read_u16_d16_hi v147, v123 offset:18000
	s_waitcnt lgkmcnt(14)
	v_fma_f32 v150, -v152, v127, v152
	v_add_f32_e32 v152, v150, v135
	v_mul_f32_e32 v171, v152, v143
	ds_read_u16_d16_hi v132, v121 offset:18400
	ds_read_u16_d16_hi v140, v122 offset:18400
	ds_read_u16_d16_hi v148, v123 offset:18400
	v_cvt_pk_bf16_f32 v151, v170, v171
	ds_write_b32 v124, v151 offset:16000
	s_waitcnt lgkmcnt(15)
	v_fma_f32 v150, -v152, v128, v152
	v_add_f32_e32 v152, v150, v136
	v_mul_f32_e32 v170, v152, v144
	ds_read_u16_d16_hi v133, v121 offset:18800
	ds_read_u16_d16_hi v141, v122 offset:18800
	ds_read_u16_d16_hi v149, v123 offset:18800
	s_waitcnt lgkmcnt(14)
	v_fma_f32 v150, -v152, v129, v152
	v_add_f32_e32 v152, v150, v137
	v_mul_f32_e32 v171, v152, v145
	ds_read_u16_d16_hi v126, v121 offset:19200
	ds_read_u16_d16_hi v134, v122 offset:19200
	ds_read_u16_d16_hi v142, v123 offset:19200
	v_cvt_pk_bf16_f32 v151, v170, v171
	ds_write_b32 v124, v151 offset:16800
	s_waitcnt lgkmcnt(15)
	v_fma_f32 v150, -v152, v130, v152
	v_add_f32_e32 v152, v150, v138
	v_mul_f32_e32 v170, v152, v146
	ds_read_u16_d16_hi v127, v121 offset:19600
	ds_read_u16_d16_hi v135, v122 offset:19600
	ds_read_u16_d16_hi v143, v123 offset:19600
	s_waitcnt lgkmcnt(14)
	v_fma_f32 v150, -v152, v131, v152
	v_add_f32_e32 v152, v150, v139
	v_mul_f32_e32 v171, v152, v147
	ds_read_u16_d16_hi v128, v121 offset:20000
	ds_read_u16_d16_hi v136, v122 offset:20000
	ds_read_u16_d16_hi v144, v123 offset:20000
	v_cvt_pk_bf16_f32 v151, v170, v171
	ds_write_b32 v124, v151 offset:17600
	s_waitcnt lgkmcnt(15)
	v_fma_f32 v150, -v152, v132, v152
	v_add_f32_e32 v152, v150, v140
	v_mul_f32_e32 v170, v152, v148
	ds_read_u16_d16_hi v129, v121 offset:20400
	ds_read_u16_d16_hi v137, v122 offset:20400
	ds_read_u16_d16_hi v145, v123 offset:20400
	s_waitcnt lgkmcnt(14)
	v_fma_f32 v150, -v152, v133, v152
	v_add_f32_e32 v152, v150, v141
	v_mul_f32_e32 v171, v152, v149
	ds_read_u16_d16_hi v130, v121 offset:20800
	ds_read_u16_d16_hi v138, v122 offset:20800
	ds_read_u16_d16_hi v146, v123 offset:20800
	v_cvt_pk_bf16_f32 v151, v170, v171
	ds_write_b32 v124, v151 offset:18400
	s_waitcnt lgkmcnt(15)
	v_fma_f32 v150, -v152, v126, v152
	v_add_f32_e32 v152, v150, v134
	v_mul_f32_e32 v170, v152, v142
	ds_read_u16_d16_hi v131, v121 offset:21200
	ds_read_u16_d16_hi v139, v122 offset:21200
	ds_read_u16_d16_hi v147, v123 offset:21200
	s_waitcnt lgkmcnt(14)
; #define LAS __attribute__((address_space(3)))
; DI unsigned pk2(float a, float b) { f32x2 v = {a, b}; bf2_t r = __builtin_convertvector(v, bf2_t); return __builtin_bit_cast(unsigned, r); }
; DI void phase_rglru(const Params& p, unsigned char* shm) {
;     ...
;             if (tid < 192) {
; #pragma unroll 8
;                 for (int r = 0; r < 64; ++r) {
;                     const float om = __uint_as_float((unsigned)*(const LAS bf16_t*)(lds + LAo + r * TR + tid * 2) << 16);
;                     const float bt = __uint_as_float((unsigned)*(const LAS bf16_t*)(lds + BTo + r * TR + tid * 2) << 16);
;                     const float g = __uint_as_float((unsigned)*(const LAS bf16_t*)(lds + GT + r * TR + tid * 2) << 16);
;                     hst = (hst - om * hst) + bt;
;                     *(LAS bf16_t*)(lds + GT + r * TR + tid * 2) = (bf16_t)(pk2(hst * g, 0.f) & 0xffffu);
;                 }
	v_fma_f32 v150, -v152, v127, v152
	v_add_f32_e32 v152, v150, v135
	v_mul_f32_e32 v171, v152, v143
	ds_read_u16_d16_hi v132, v121 offset:21600
	ds_read_u16_d16_hi v140, v122 offset:21600
	ds_read_u16_d16_hi v148, v123 offset:21600
	v_cvt_pk_bf16_f32 v151, v170, v171
	ds_write_b32 v124, v151 offset:19200
	s_waitcnt lgkmcnt(15)
	v_fma_f32 v150, -v152, v128, v152
	v_add_f32_e32 v152, v150, v136
	v_mul_f32_e32 v170, v152, v144
	ds_read_u16_d16_hi v133, v121 offset:22000
	ds_read_u16_d16_hi v141, v122 offset:22000
	ds_read_u16_d16_hi v149, v123 offset:22000
	s_waitcnt lgkmcnt(14)
	v_fma_f32 v150, -v152, v129, v152
	v_add_f32_e32 v152, v150, v137
	v_mul_f32_e32 v171, v152, v145
	ds_read_u16_d16_hi v126, v121 offset:22400
	ds_read_u16_d16_hi v134, v122 offset:22400
	ds_read_u16_d16_hi v142, v123 offset:22400
	v_cvt_pk_bf16_f32 v151, v170, v171
	ds_write_b32 v124, v151 offset:20000
	s_waitcnt lgkmcnt(15)
	v_fma_f32 v150, -v152, v130, v152
	v_add_f32_e32 v152, v150, v138
	v_mul_f32_e32 v170, v152, v146
	ds_read_u16_d16_hi v127, v121 offset:22800
	ds_read_u16_d16_hi v135, v122 offset:22800
	ds_read_u16_d16_hi v143, v123 offset:22800
	s_waitcnt lgkmcnt(14)
	v_fma_f32 v150, -v152, v131, v152
	v_add_f32_e32 v152, v150, v139
	v_mul_f32_e32 v171, v152, v147
	ds_read_u16_d16_hi v128, v121 offset:23200
	ds_read_u16_d16_hi v136, v122 offset:23200
	ds_read_u16_d16_hi v144, v123 offset:23200
	v_cvt_pk_bf16_f32 v151, v170, v171
	ds_write_b32 v124, v151 offset:20800
	s_waitcnt lgkmcnt(15)
	v_fma_f32 v150, -v152, v132, v152
	v_add_f32_e32 v152, v150, v140
	v_mul_f32_e32 v170, v152, v148
	ds_read_u16_d16_hi v129, v121 offset:23600
	ds_read_u16_d16_hi v137, v122 offset:23600
	ds_read_u16_d16_hi v145, v123 offset:23600
	s_waitcnt lgkmcnt(14)
	v_fma_f32 v150, -v152, v133, v152
	v_add_f32_e32 v152, v150, v141
	v_mul_f32_e32 v171, v152, v149
	ds_read_u16_d16_hi v130, v121 offset:24000
	ds_read_u16_d16_hi v138, v122 offset:24000
	ds_read_u16_d16_hi v146, v123 offset:24000
	v_cvt_pk_bf16_f32 v151, v170, v171
	ds_write_b32 v124, v151 offset:21600
	s_waitcnt lgkmcnt(15)
	v_fma_f32 v150, -v152, v126, v152
	v_add_f32_e32 v152, v150, v134
	v_mul_f32_e32 v170, v152, v142
	ds_read_u16_d16_hi v131, v121 offset:24400
	ds_read_u16_d16_hi v139, v122 offset:24400
	ds_read_u16_d16_hi v147, v123 offset:24400
	s_waitcnt lgkmcnt(14)
	v_fma_f32 v150, -v152, v127, v152
	v_add_f32_e32 v152, v150, v135
	v_mul_f32_e32 v171, v152, v143
	ds_read_u16_d16_hi v132, v121 offset:24800
	ds_read_u16_d16_hi v140, v122 offset:24800
	ds_read_u16_d16_hi v148, v123 offset:24800
	v_cvt_pk_bf16_f32 v151, v170, v171
	ds_write_b32 v124, v151 offset:22400
	s_waitcnt lgkmcnt(15)
	v_fma_f32 v150, -v152, v128, v152
	v_add_f32_e32 v152, v150, v136
	v_mul_f32_e32 v170, v152, v144
	ds_read_u16_d16_hi v133, v121 offset:25200
	ds_read_u16_d16_hi v141, v122 offset:25200
	ds_read_u16_d16_hi v149, v123 offset:25200
	s_waitcnt lgkmcnt(14)
	v_fma_f32 v150, -v152, v129, v152
	v_add_f32_e32 v152, v150, v137
	v_mul_f32_e32 v171, v152, v145
	v_cvt_pk_bf16_f32 v151, v170, v171
	ds_write_b32 v124, v151 offset:23200
	s_waitcnt lgkmcnt(12)
	v_fma_f32 v150, -v152, v130, v152
	v_add_f32_e32 v152, v150, v138
	v_mul_f32_e32 v170, v152, v146
	s_waitcnt lgkmcnt(8)
	v_fma_f32 v150, -v152, v131, v152
	v_add_f32_e32 v152, v150, v139
	v_mul_f32_e32 v171, v152, v147
	v_cvt_pk_bf16_f32 v151, v170, v171
	ds_write_b32 v124, v151 offset:24000
	s_waitcnt lgkmcnt(6)
	v_fma_f32 v150, -v152, v132, v152
	v_add_f32_e32 v152, v150, v140
	v_mul_f32_e32 v170, v152, v148
	s_waitcnt lgkmcnt(2)
	v_fma_f32 v150, -v152, v133, v152
	v_add_f32_e32 v152, v150, v141
	v_mul_f32_e32 v171, v152, v149
	v_cvt_pk_bf16_f32 v151, v170, v171
	ds_write_b32 v124, v151 offset:24800
	s_branch .LBB0_842
